# k16 + NA loop: bias-load wait counted (vmcnt(4)) so the next tile's LDS-DMA is not drained before QK; NA next-tile DMA unconditional
# speedup vs baseline: 1.0039x; 1.0039x over previous
; #define SBAR() __builtin_amdgcn_sched_barrier(0)
; #define NPUB() do { asm volatile("s_waitcnt vmcnt(0)" ::: "memory"); __syncthreads(); } while (0)
; template <bool NA> __device__ __forceinline__ void acc_init(f32x16& p0, f32x16& p1, int j, const Unit& U, int wid, int r32, int hi) {
;   if constexpr (!NA) { p0 = f32x16{}; p1 = f32x16{}; }
;   else {
;     int slice = 16;
;     if (j >= U.nsplit) { const int kr = U.kr0 + (j - U.nsplit), qr_ = U.qrow0 + (wid >> 1); int rs = qr_ - 4; rs = rs < 0 ? 0 : (rs > 248 ? 248 : rs);
;       slice = (kr >= rs && kr < rs + 8) ? (kr - qr_ + 7) : 15; }
;     const float* tb = U.natab + (size_t)slice * 4096 + (unsigned)(((wid & 1) * 32 + r32) * 64 + 4 * hi);
; #pragma unroll
;     for (int q = 0; q < 4; ++q) { const f32x4 a = *(const f32x4*)(tb + 8 * q), b = *(const f32x4*)(tb + 32 + 8 * q);
;       p0[4 * q + 0] = a[0]; p0[4 * q + 1] = a[1]; p0[4 * q + 2] = a[2]; p0[4 * q + 3] = a[3];
;       p1[4 * q + 0] = b[0]; p1[4 * q + 1] = b[1]; p1[4 * q + 2] = b[2]; p1[4 * q + 3] = b[3]; }
;   }
; }
; template <bool NA> __device__ __forceinline__ void unit_body_v128(const Unit& U, char* lds) {
;     ...
;   const int NT = U.nt;
;   NDMA(0, 0); NPUB();
;   for (int j = 0; j < NT; j += 2) {
;     f32x16 p0, p1;
;     acc_init<NA>(p0, p1, j, U, wid, r32, hi); SBAR();
;     NDMA(j + 1, 1); SBAR();
;     NTILE(0); SBAR(); NPUB();
.LBB0_385:
	v_lshl_add_u64 v[78:79], s[6:7], 2, v[136:137]
	global_load_dwordx4 v[82:85], v[78:79], off
	global_load_dwordx4 v[86:89], v[78:79], off offset:32
	global_load_dwordx4 v[66:69], v[78:79], off offset:128
	global_load_dwordx4 v[70:73], v[78:79], off offset:160
	global_load_dwordx4 v[90:93], v[78:79], off offset:64
	global_load_dwordx4 v[94:97], v[78:79], off offset:96
	global_load_dwordx4 v[74:77], v[78:79], off offset:192
	s_nop 0
	global_load_dwordx4 v[78:81], v[78:79], off offset:224
	s_add_i32 s6, s9, 1
	s_cmp_ge_u32 s6, s24
	s_cselect_b64 s[82:83], -1, 0
	s_add_i32 s9, s8, s91
	s_cmp_lt_u32 s6, s24
	s_cselect_b32 s6, s91, s9
	s_sub_i32 s6, s6, 64
	s_mul_i32 s84, s6, 0x3000
	s_mul_hi_i32 s85, s6, 0x3000
	s_add_u32 s6, s46, s84
	s_addc_u32 s7, s47, s85
	s_add_u32 s84, s22, s84
	s_addc_u32 s85, s23, s85
	v_lshl_add_u64 v[156:157], v[0:1], 1, s[6:7]
	s_add_i32 m0, s62, s29
	s_nop 0
	global_load_lds_dwordx4 v[156:157], off
	v_lshl_add_u64 v[156:157], v[130:131], 1, s[84:85]
	s_add_i32 m0, s30, 0x8000
	s_nop 0
	global_load_lds_dwordx4 v[156:157], off
	v_lshl_add_u64 v[156:157], v[132:133], 1, s[6:7]
	s_add_i32 m0, s62, s31
	s_nop 0
	global_load_lds_dwordx4 v[156:157], off
	v_lshl_add_u64 v[156:157], v[134:135], 1, s[84:85]
	s_add_i32 m0, s30, 0x8400
	s_nop 0
	global_load_lds_dwordx4 v[156:157], off
	s_waitcnt lgkmcnt(0)
	ds_read_b128 v[156:159], v143 offset:0
	ds_read_b128 v[160:163], v143 offset:0x2000
	ds_read_b128 v[164:167], v144 offset:0
	ds_read_b128 v[168:171], v144 offset:0x2000
	s_waitcnt lgkmcnt(2)
	s_waitcnt vmcnt(4)
	v_mfma_f32_32x32x16_bf16 v[82:97], v[156:159], v[98:101], v[82:97]
	v_mfma_f32_32x32x16_bf16 v[66:81], v[160:163], v[98:101], v[66:81]
	ds_read_b128 v[156:159], v145 offset:0
	ds_read_b128 v[160:163], v145 offset:0x2000
	s_waitcnt lgkmcnt(2)
	v_mfma_f32_32x32x16_bf16 v[82:97], v[164:167], v[102:105], v[82:97]
	v_mfma_f32_32x32x16_bf16 v[66:81], v[168:171], v[102:105], v[66:81]
	ds_read_b128 v[164:167], v147 offset:0
	ds_read_b128 v[168:171], v147 offset:0x2000
	s_waitcnt lgkmcnt(2)
	v_mfma_f32_32x32x16_bf16 v[82:97], v[156:159], v[106:109], v[82:97]
	v_mfma_f32_32x32x16_bf16 v[66:81], v[160:163], v[106:109], v[66:81]
	ds_read_b128 v[156:159], v148 offset:0
	ds_read_b128 v[160:163], v148 offset:0x2000
	s_waitcnt lgkmcnt(2)
	v_mfma_f32_32x32x16_bf16 v[82:97], v[164:167], v[110:113], v[82:97]
	v_mfma_f32_32x32x16_bf16 v[66:81], v[168:171], v[110:113], v[66:81]
	ds_read_b128 v[164:167], v149 offset:0
	ds_read_b128 v[168:171], v149 offset:0x2000
	s_waitcnt lgkmcnt(2)
	v_mfma_f32_32x32x16_bf16 v[82:97], v[156:159], v[114:117], v[82:97]
	v_mfma_f32_32x32x16_bf16 v[66:81], v[160:163], v[114:117], v[66:81]
	ds_read_b128 v[156:159], v150 offset:0
	ds_read_b128 v[160:163], v150 offset:0x2000
	s_waitcnt lgkmcnt(2)
	v_mfma_f32_32x32x16_bf16 v[82:97], v[164:167], v[118:121], v[82:97]
	v_mfma_f32_32x32x16_bf16 v[66:81], v[168:171], v[118:121], v[66:81]
	ds_read_b128 v[164:167], v151 offset:0
	ds_read_b128 v[168:171], v151 offset:0x2000
	s_waitcnt lgkmcnt(2)
	v_mfma_f32_32x32x16_bf16 v[82:97], v[156:159], v[122:125], v[82:97]
	v_mfma_f32_32x32x16_bf16 v[66:81], v[160:163], v[122:125], v[66:81]
	s_waitcnt lgkmcnt(0)
	v_mfma_f32_32x32x16_bf16 v[82:97], v[164:167], v[126:129], v[82:97]
	v_mfma_f32_32x32x16_bf16 v[66:81], v[168:171], v[126:129], v[66:81]
	s_nop 10
	v_max_f32_e32 v154, v83, v83
	v_max_f32_e32 v156, v82, v82
	v_max_f32_e32 v154, v156, v154
	v_max3_f32 v154, v154, v84, v85
	v_max3_f32 v154, v154, v86, v87
	v_max3_f32 v154, v154, v88, v89
	v_max3_f32 v154, v154, v90, v91
	v_max3_f32 v154, v154, v92, v93
	v_max3_f32 v154, v154, v94, v95
	v_max3_f32 v154, v154, v96, v97
	v_max3_f32 v154, v154, v66, v67
	v_max3_f32 v154, v154, v68, v69
	v_max3_f32 v154, v154, v70, v71
	v_max3_f32 v154, v154, v72, v73
	v_max3_f32 v154, v154, v74, v75
	v_max3_f32 v154, v154, v76, v77
	v_max3_f32 v154, v154, v78, v79
	v_max3_f32 v154, v154, v80, v81
	v_mov_b32_e32 v156, v154
	s_nop 1
	v_permlane32_swap_b32_e32 v154, v156
	v_max_f32_e32 v156, v156, v156
	v_max_f32_e32 v154, v154, v154
	v_max_f32_e32 v154, v154, v156
	v_sub_f32_e32 v156, v154, v155
	v_cmp_ge_f32_e32 vcc, s63, v156
	v_max_f32_e32 v156, v155, v155
	v_max_f32_e32 v156, v156, v154
	v_sub_f32_e32 v154, v155, v156
	v_mul_f32_e32 v154, 0x3e0293ee, v154
	v_exp_f32_e32 v154, v154
	s_cmp_eq_u64 vcc, exec
	s_cselect_b64 s[6:7], -1, 0
	v_cndmask_b32_e64 v154, v154, 1.0, s[6:7]
	v_cmp_gt_f32_e32 vcc, 1.0, v154
	s_cbranch_vccz .LBB0_389
	s_and_saveexec_b64 s[84:85], s[4:5]
	ds_write_b32 v146, v154 offset:128
	s_or_b64 exec, exec, s[84:85]
	s_waitcnt lgkmcnt(0)
	ds_read_b128 v[158:161], v138 offset:224
	ds_read_b128 v[162:165], v138 offset:192
	ds_read_b128 v[166:169], v138 offset:160
	ds_read_b128 v[170:173], v138 offset:128
	s_waitcnt lgkmcnt(0)
	v_pk_mul_f32 v[16:17], v[16:17], v[160:161]
	v_pk_mul_f32 v[12:13], v[12:13], v[164:165]
	v_pk_mul_f32 v[8:9], v[8:9], v[168:169]
	v_pk_mul_f32 v[4:5], v[4:5], v[172:173]
	v_pk_mul_f32 v[14:15], v[14:15], v[158:159]
	v_pk_mul_f32 v[10:11], v[10:11], v[162:163]
	v_pk_mul_f32 v[6:7], v[6:7], v[166:167]
	v_pk_mul_f32 v[2:3], v[2:3], v[170:171]
	v_pk_mul_f32 v[64:65], v[64:65], v[160:161]
	v_pk_mul_f32 v[60:61], v[60:61], v[164:165]
	v_pk_mul_f32 v[56:57], v[56:57], v[168:169]
	v_pk_mul_f32 v[52:53], v[52:53], v[172:173]
	v_pk_mul_f32 v[62:63], v[62:63], v[158:159]
	v_pk_mul_f32 v[58:59], v[58:59], v[162:163]
	v_pk_mul_f32 v[54:55], v[54:55], v[166:167]
	v_pk_mul_f32 v[50:51], v[50:51], v[170:171]
	v_pk_mul_f32 v[48:49], v[48:49], v[160:161]
	v_pk_mul_f32 v[44:45], v[44:45], v[164:165]
	v_pk_mul_f32 v[40:41], v[40:41], v[168:169]
	v_pk_mul_f32 v[36:37], v[36:37], v[172:173]
	v_pk_mul_f32 v[46:47], v[46:47], v[158:159]
	v_pk_mul_f32 v[42:43], v[42:43], v[162:163]
	v_pk_mul_f32 v[38:39], v[38:39], v[166:167]
	v_pk_mul_f32 v[34:35], v[34:35], v[170:171]
	v_pk_mul_f32 v[32:33], v[32:33], v[160:161]
	v_pk_mul_f32 v[28:29], v[28:29], v[164:165]
	v_pk_mul_f32 v[24:25], v[24:25], v[168:169]
	v_pk_mul_f32 v[20:21], v[20:21], v[172:173]
	v_pk_mul_f32 v[30:31], v[30:31], v[158:159]
	v_pk_mul_f32 v[26:27], v[26:27], v[162:163]
	v_pk_mul_f32 v[22:23], v[22:23], v[166:167]
	v_pk_mul_f32 v[18:19], v[18:19], v[170:171]

; #define SBAR() __builtin_amdgcn_sched_barrier(0)
; #define NPUB() do { asm volatile("s_waitcnt vmcnt(0)" ::: "memory"); __syncthreads(); } while (0)
; template <bool NA> __device__ __forceinline__ void acc_init(f32x16& p0, f32x16& p1, int j, const Unit& U, int wid, int r32, int hi) {
;   if constexpr (!NA) { p0 = f32x16{}; p1 = f32x16{}; }
;   else {
;     int slice = 16;
;     if (j >= U.nsplit) { const int kr = U.kr0 + (j - U.nsplit), qr_ = U.qrow0 + (wid >> 1); int rs = qr_ - 4; rs = rs < 0 ? 0 : (rs > 248 ? 248 : rs);
;       slice = (kr >= rs && kr < rs + 8) ? (kr - qr_ + 7) : 15; }
;     const float* tb = U.natab + (size_t)slice * 4096 + (unsigned)(((wid & 1) * 32 + r32) * 64 + 4 * hi);
; #pragma unroll
;     for (int q = 0; q < 4; ++q) { const f32x4 a = *(const f32x4*)(tb + 8 * q), b = *(const f32x4*)(tb + 32 + 8 * q);
;       p0[4 * q + 0] = a[0]; p0[4 * q + 1] = a[1]; p0[4 * q + 2] = a[2]; p0[4 * q + 3] = a[3];
;       p1[4 * q + 0] = b[0]; p1[4 * q + 1] = b[1]; p1[4 * q + 2] = b[2]; p1[4 * q + 3] = b[3]; }
;   }
; }
; template <bool NA> __device__ __forceinline__ void unit_body_v128(const Unit& U, char* lds) {
;     ...
;   const int NT = U.nt;
;   NDMA(0, 0); NPUB();
;   for (int j = 0; j < NT; j += 2) {
;     f32x16 p0, p1;
;     acc_init<NA>(p0, p1, j, U, wid, r32, hi); SBAR();
;     NDMA(j + 1, 1); SBAR();
;     NTILE(0); SBAR(); NPUB();
;     acc_init<NA>(p0, p1, j + 1, U, wid, r32, hi); SBAR();
;     if (j + 2 < NT) NDMA(j + 2, 0); SBAR();
;     NTILE(1); SBAR(); NPUB();
.LBB0_391:
	v_lshl_add_u64 v[78:79], s[6:7], 2, v[136:137]
	global_load_dwordx4 v[82:85], v[78:79], off
	global_load_dwordx4 v[86:89], v[78:79], off offset:32
	global_load_dwordx4 v[66:69], v[78:79], off offset:128
	global_load_dwordx4 v[70:73], v[78:79], off offset:160
	global_load_dwordx4 v[90:93], v[78:79], off offset:64
	global_load_dwordx4 v[94:97], v[78:79], off offset:96
	global_load_dwordx4 v[74:77], v[78:79], off offset:192
	s_nop 0
	global_load_dwordx4 v[78:81], v[78:79], off offset:224
	s_cmp_ge_u32 s90, s0
	s_cselect_b64 s[82:83], -1, 0
	s_and_b64 vcc, exec, s[82:83]
	s_cmp_lt_u32 s90, s24
	s_cselect_b32 s6, s91, s9
	s_mul_i32 s84, s6, 0x3000
	s_mul_hi_i32 s9, s6, 0x3000
	s_add_u32 s6, s46, s84
	s_addc_u32 s7, s47, s9
	s_add_u32 s84, s22, s84
	s_mov_b32 m0, s67
	s_addc_u32 s85, s23, s9
	v_lshl_add_u64 v[158:159], v[0:1], 1, s[6:7]
	global_load_lds_dwordx4 v[158:159], off
	v_lshl_add_u64 v[158:159], v[130:131], 1, s[84:85]
	s_mov_b32 m0, s30
	s_nop 0
	global_load_lds_dwordx4 v[158:159], off
	v_lshl_add_u64 v[158:159], v[132:133], 1, s[6:7]
	s_mov_b32 m0, s33
	s_nop 0
	global_load_lds_dwordx4 v[158:159], off
	v_lshl_add_u64 v[158:159], v[134:135], 1, s[84:85]
	s_mov_b32 m0, s35
	s_nop 0
	global_load_lds_dwordx4 v[158:159], off
.LBB0_393:
	s_waitcnt lgkmcnt(0)
	ds_read_b128 v[158:161], v143 offset:0x4000
	ds_read_b128 v[162:165], v143 offset:0x6000
	ds_read_b128 v[166:169], v144 offset:0x4000
	ds_read_b128 v[170:173], v144 offset:0x6000
	s_waitcnt lgkmcnt(2)
	s_waitcnt vmcnt(4)
	v_mfma_f32_32x32x16_bf16 v[82:97], v[158:161], v[98:101], v[82:97]
	v_mfma_f32_32x32x16_bf16 v[66:81], v[162:165], v[98:101], v[66:81]
	ds_read_b128 v[158:161], v145 offset:0x4000
	ds_read_b128 v[162:165], v145 offset:0x6000
	s_waitcnt lgkmcnt(2)
	v_mfma_f32_32x32x16_bf16 v[82:97], v[166:169], v[102:105], v[82:97]
	v_mfma_f32_32x32x16_bf16 v[66:81], v[170:173], v[102:105], v[66:81]
	ds_read_b128 v[166:169], v147 offset:0x4000
	ds_read_b128 v[170:173], v147 offset:0x6000
	s_waitcnt lgkmcnt(2)
	v_mfma_f32_32x32x16_bf16 v[82:97], v[158:161], v[106:109], v[82:97]
	v_mfma_f32_32x32x16_bf16 v[66:81], v[162:165], v[106:109], v[66:81]
	ds_read_b128 v[158:161], v148 offset:0x4000
	ds_read_b128 v[162:165], v148 offset:0x6000
	s_waitcnt lgkmcnt(2)
	v_mfma_f32_32x32x16_bf16 v[82:97], v[166:169], v[110:113], v[82:97]
	v_mfma_f32_32x32x16_bf16 v[66:81], v[170:173], v[110:113], v[66:81]
	ds_read_b128 v[166:169], v149 offset:0x4000
	ds_read_b128 v[170:173], v149 offset:0x6000
	s_waitcnt lgkmcnt(2)
	v_mfma_f32_32x32x16_bf16 v[82:97], v[158:161], v[114:117], v[82:97]
	v_mfma_f32_32x32x16_bf16 v[66:81], v[162:165], v[114:117], v[66:81]
	ds_read_b128 v[158:161], v150 offset:0x4000
	ds_read_b128 v[162:165], v150 offset:0x6000
	s_waitcnt lgkmcnt(2)
	v_mfma_f32_32x32x16_bf16 v[82:97], v[166:169], v[118:121], v[82:97]
	v_mfma_f32_32x32x16_bf16 v[66:81], v[170:173], v[118:121], v[66:81]
	ds_read_b128 v[166:169], v151 offset:0x4000
	ds_read_b128 v[170:173], v151 offset:0x6000
	s_waitcnt lgkmcnt(2)
	v_mfma_f32_32x32x16_bf16 v[82:97], v[158:161], v[122:125], v[82:97]
	v_mfma_f32_32x32x16_bf16 v[66:81], v[162:165], v[122:125], v[66:81]
	s_waitcnt lgkmcnt(0)
	v_mfma_f32_32x32x16_bf16 v[82:97], v[166:169], v[126:129], v[82:97]
	v_mfma_f32_32x32x16_bf16 v[66:81], v[170:173], v[126:129], v[66:81]
	s_nop 10
	v_max_f32_e32 v158, v83, v83
	v_max_f32_e32 v159, v82, v82
	v_max_f32_e32 v158, v159, v158
	v_max3_f32 v158, v158, v84, v85
	v_max3_f32 v158, v158, v86, v87
	v_max3_f32 v158, v158, v88, v89
	v_max3_f32 v158, v158, v90, v91
	v_max3_f32 v158, v158, v92, v93
	v_max3_f32 v158, v158, v94, v95
	v_max3_f32 v158, v158, v96, v97
	v_max3_f32 v158, v158, v66, v67
	v_max3_f32 v158, v158, v68, v69
	v_max3_f32 v158, v158, v70, v71
	v_max3_f32 v158, v158, v72, v73
	v_max3_f32 v158, v158, v74, v75
	v_max3_f32 v158, v158, v76, v77
	v_max3_f32 v158, v158, v78, v79
	v_max3_f32 v158, v158, v80, v81
	v_mov_b32_e32 v159, v158
	s_nop 1
	v_permlane32_swap_b32_e32 v158, v159
	v_max_f32_e32 v159, v159, v159
	v_max_f32_e32 v158, v158, v158
	v_max_f32_e32 v158, v158, v159
	v_sub_f32_e32 v159, v158, v155
	v_cmp_ge_f32_e32 vcc, s63, v159
	v_max_f32_e32 v159, v155, v155
	v_max_f32_e32 v159, v159, v158
	v_sub_f32_e32 v158, v155, v159
	v_mul_f32_e32 v158, 0x3e0293ee, v158
	v_exp_f32_e32 v158, v158
	s_cmp_eq_u64 vcc, exec
	s_cselect_b64 s[6:7], -1, 0
	v_cndmask_b32_e64 v158, v158, 1.0, s[6:7]
	v_cmp_gt_f32_e32 vcc, 1.0, v158
	s_cbranch_vccz .LBB0_382
	s_and_saveexec_b64 s[84:85], s[4:5]
	s_cbranch_execz .LBB0_381
	ds_write_b32 v146, v158 offset:128
	s_branch .LBB0_381

; #define SBAR() __builtin_amdgcn_sched_barrier(0)
; #define NPUB() do { asm volatile("s_waitcnt vmcnt(0)" ::: "memory"); __syncthreads(); } while (0)
; template <bool NA> __device__ __forceinline__ void acc_init(f32x16& p0, f32x16& p1, int j, const Unit& U, int wid, int r32, int hi) {
;   if constexpr (!NA) { p0 = f32x16{}; p1 = f32x16{}; }
;   else {
;     int slice = 16;
;     if (j >= U.nsplit) { const int kr = U.kr0 + (j - U.nsplit), qr_ = U.qrow0 + (wid >> 1); int rs = qr_ - 4; rs = rs < 0 ? 0 : (rs > 248 ? 248 : rs);
;       slice = (kr >= rs && kr < rs + 8) ? (kr - qr_ + 7) : 15; }
;     const float* tb = U.natab + (size_t)slice * 4096 + (unsigned)(((wid & 1) * 32 + r32) * 64 + 4 * hi);
; #pragma unroll
;     for (int q = 0; q < 4; ++q) { const f32x4 a = *(const f32x4*)(tb + 8 * q), b = *(const f32x4*)(tb + 32 + 8 * q);
;       p0[4 * q + 0] = a[0]; p0[4 * q + 1] = a[1]; p0[4 * q + 2] = a[2]; p0[4 * q + 3] = a[3];
;       p1[4 * q + 0] = b[0]; p1[4 * q + 1] = b[1]; p1[4 * q + 2] = b[2]; p1[4 * q + 3] = b[3]; }
;   }
; }
; template <bool NA> __device__ __forceinline__ void unit_body_v128(const Unit& U, char* lds) {
;     ...
;   const int NT = U.nt;
;   NDMA(0, 0); NPUB();
;   for (int j = 0; j < NT; j += 2) {
;     f32x16 p0, p1;
;     acc_init<NA>(p0, p1, j, U, wid, r32, hi); SBAR();
;     NDMA(j + 1, 1); SBAR();
;     NTILE(0); SBAR(); NPUB();
.LBB0_1415:
	v_lshl_add_u64 v[78:79], s[6:7], 2, v[136:137]
	global_load_dwordx4 v[82:85], v[78:79], off
	global_load_dwordx4 v[86:89], v[78:79], off offset:32
	global_load_dwordx4 v[66:69], v[78:79], off offset:128
	global_load_dwordx4 v[70:73], v[78:79], off offset:160
	global_load_dwordx4 v[90:93], v[78:79], off offset:64
	global_load_dwordx4 v[94:97], v[78:79], off offset:96
	global_load_dwordx4 v[74:77], v[78:79], off offset:192
	s_nop 0
	global_load_dwordx4 v[78:81], v[78:79], off offset:224
	s_add_i32 s6, s58, 1
	s_cmp_ge_u32 s6, s28
	s_cselect_b64 s[80:81], -1, 0
	s_add_i32 s58, s59, s5
	s_cmp_lt_u32 s6, s28
	s_cselect_b32 s6, s5, s58
	s_sub_i32 s6, s6, 64
	s_mul_i32 s82, s6, 0x3000
	s_mul_hi_i32 s83, s6, 0x3000
	s_add_u32 s6, s24, s82
	s_addc_u32 s7, s25, s83
	s_add_u32 s82, s22, s82
	s_addc_u32 s83, s23, s83
	v_lshl_add_u64 v[156:157], v[0:1], 1, s[6:7]
	s_add_i32 m0, s94, s29
	s_nop 0
	global_load_lds_dwordx4 v[156:157], off
	v_lshl_add_u64 v[156:157], v[130:131], 1, s[82:83]
	s_add_i32 m0, s30, 0x8000
	s_nop 0
	global_load_lds_dwordx4 v[156:157], off
	v_lshl_add_u64 v[156:157], v[132:133], 1, s[6:7]
	s_add_i32 m0, s94, s31
	s_nop 0
	global_load_lds_dwordx4 v[156:157], off
	v_lshl_add_u64 v[156:157], v[134:135], 1, s[82:83]
	s_add_i32 m0, s30, 0x8400
	s_nop 0
	global_load_lds_dwordx4 v[156:157], off
	s_waitcnt lgkmcnt(0)
	ds_read_b128 v[156:159], v143 offset:0
	ds_read_b128 v[160:163], v143 offset:0x2000
	ds_read_b128 v[164:167], v144 offset:0
	ds_read_b128 v[168:171], v144 offset:0x2000
	s_waitcnt lgkmcnt(2)
	s_waitcnt vmcnt(4)
	v_mfma_f32_32x32x16_bf16 v[82:97], v[156:159], v[98:101], v[82:97]
	v_mfma_f32_32x32x16_bf16 v[66:81], v[160:163], v[98:101], v[66:81]
	ds_read_b128 v[156:159], v145 offset:0
	ds_read_b128 v[160:163], v145 offset:0x2000
	s_waitcnt lgkmcnt(2)
	v_mfma_f32_32x32x16_bf16 v[82:97], v[164:167], v[102:105], v[82:97]
	v_mfma_f32_32x32x16_bf16 v[66:81], v[168:171], v[102:105], v[66:81]
	ds_read_b128 v[164:167], v147 offset:0
	ds_read_b128 v[168:171], v147 offset:0x2000
	s_waitcnt lgkmcnt(2)
	v_mfma_f32_32x32x16_bf16 v[82:97], v[156:159], v[106:109], v[82:97]
	v_mfma_f32_32x32x16_bf16 v[66:81], v[160:163], v[106:109], v[66:81]
	ds_read_b128 v[156:159], v148 offset:0
	ds_read_b128 v[160:163], v148 offset:0x2000
	s_waitcnt lgkmcnt(2)
	v_mfma_f32_32x32x16_bf16 v[82:97], v[164:167], v[110:113], v[82:97]
	v_mfma_f32_32x32x16_bf16 v[66:81], v[168:171], v[110:113], v[66:81]
	ds_read_b128 v[164:167], v149 offset:0
	ds_read_b128 v[168:171], v149 offset:0x2000
	s_waitcnt lgkmcnt(2)
	v_mfma_f32_32x32x16_bf16 v[82:97], v[156:159], v[114:117], v[82:97]
	v_mfma_f32_32x32x16_bf16 v[66:81], v[160:163], v[114:117], v[66:81]
	ds_read_b128 v[156:159], v150 offset:0
	ds_read_b128 v[160:163], v150 offset:0x2000
	s_waitcnt lgkmcnt(2)
	v_mfma_f32_32x32x16_bf16 v[82:97], v[164:167], v[118:121], v[82:97]
	v_mfma_f32_32x32x16_bf16 v[66:81], v[168:171], v[118:121], v[66:81]
	ds_read_b128 v[164:167], v151 offset:0
	ds_read_b128 v[168:171], v151 offset:0x2000
	s_waitcnt lgkmcnt(2)
	v_mfma_f32_32x32x16_bf16 v[82:97], v[156:159], v[122:125], v[82:97]
	v_mfma_f32_32x32x16_bf16 v[66:81], v[160:163], v[122:125], v[66:81]
	s_waitcnt lgkmcnt(0)
	v_mfma_f32_32x32x16_bf16 v[82:97], v[164:167], v[126:129], v[82:97]
	v_mfma_f32_32x32x16_bf16 v[66:81], v[168:171], v[126:129], v[66:81]
	s_nop 10
	v_max_f32_e32 v154, v83, v83
	v_max_f32_e32 v156, v82, v82
	v_max_f32_e32 v154, v156, v154
	v_max3_f32 v154, v154, v84, v85
	v_max3_f32 v154, v154, v86, v87
	v_max3_f32 v154, v154, v88, v89
	v_max3_f32 v154, v154, v90, v91
	v_max3_f32 v154, v154, v92, v93
	v_max3_f32 v154, v154, v94, v95
	v_max3_f32 v154, v154, v96, v97
	v_max3_f32 v154, v154, v66, v67
	v_max3_f32 v154, v154, v68, v69
	v_max3_f32 v154, v154, v70, v71
	v_max3_f32 v154, v154, v72, v73
	v_max3_f32 v154, v154, v74, v75
	v_max3_f32 v154, v154, v76, v77
	v_max3_f32 v154, v154, v78, v79
	v_max3_f32 v154, v154, v80, v81
	v_mov_b32_e32 v156, v154
	s_nop 1
	v_permlane32_swap_b32_e32 v154, v156
	v_max_f32_e32 v156, v156, v156
	v_max_f32_e32 v154, v154, v154
	v_max_f32_e32 v154, v154, v156
	v_sub_f32_e32 v156, v154, v155
	v_cmp_ge_f32_e32 vcc, s95, v156
	v_max_f32_e32 v156, v155, v155
	v_max_f32_e32 v156, v156, v154
	v_sub_f32_e32 v154, v155, v156
	v_mul_f32_e32 v154, 0x3e0293ee, v154
	v_exp_f32_e32 v154, v154
	s_cmp_eq_u64 vcc, exec
	s_cselect_b64 s[6:7], -1, 0
	v_cndmask_b32_e64 v154, v154, 1.0, s[6:7]
	v_cmp_gt_f32_e32 vcc, 1.0, v154
	s_cbranch_vccz .LBB0_1419
	s_and_saveexec_b64 s[82:83], s[0:1]
	ds_write_b32 v146, v154 offset:128
	s_or_b64 exec, exec, s[82:83]
	s_waitcnt lgkmcnt(0)
	ds_read_b128 v[158:161], v138 offset:224
	ds_read_b128 v[162:165], v138 offset:192
	ds_read_b128 v[166:169], v138 offset:160
	ds_read_b128 v[170:173], v138 offset:128
	s_waitcnt lgkmcnt(0)
	v_pk_mul_f32 v[16:17], v[16:17], v[160:161]
	v_pk_mul_f32 v[12:13], v[12:13], v[164:165]
	v_pk_mul_f32 v[8:9], v[8:9], v[168:169]
	v_pk_mul_f32 v[4:5], v[4:5], v[172:173]
	v_pk_mul_f32 v[14:15], v[14:15], v[158:159]
	v_pk_mul_f32 v[10:11], v[10:11], v[162:163]
	v_pk_mul_f32 v[6:7], v[6:7], v[166:167]
	v_pk_mul_f32 v[2:3], v[2:3], v[170:171]
	v_pk_mul_f32 v[64:65], v[64:65], v[160:161]
	v_pk_mul_f32 v[60:61], v[60:61], v[164:165]
	v_pk_mul_f32 v[56:57], v[56:57], v[168:169]
	v_pk_mul_f32 v[52:53], v[52:53], v[172:173]
	v_pk_mul_f32 v[62:63], v[62:63], v[158:159]
	v_pk_mul_f32 v[58:59], v[58:59], v[162:163]
	v_pk_mul_f32 v[54:55], v[54:55], v[166:167]
	v_pk_mul_f32 v[50:51], v[50:51], v[170:171]
	v_pk_mul_f32 v[48:49], v[48:49], v[160:161]
	v_pk_mul_f32 v[44:45], v[44:45], v[164:165]
	v_pk_mul_f32 v[40:41], v[40:41], v[168:169]
	v_pk_mul_f32 v[36:37], v[36:37], v[172:173]
	v_pk_mul_f32 v[46:47], v[46:47], v[158:159]
	v_pk_mul_f32 v[42:43], v[42:43], v[162:163]
	v_pk_mul_f32 v[38:39], v[38:39], v[166:167]
	v_pk_mul_f32 v[34:35], v[34:35], v[170:171]
	v_pk_mul_f32 v[32:33], v[32:33], v[160:161]
	v_pk_mul_f32 v[28:29], v[28:29], v[164:165]
	v_pk_mul_f32 v[24:25], v[24:25], v[168:169]
	v_pk_mul_f32 v[20:21], v[20:21], v[172:173]
	v_pk_mul_f32 v[30:31], v[30:31], v[158:159]
	v_pk_mul_f32 v[26:27], v[26:27], v[162:163]
	v_pk_mul_f32 v[22:23], v[22:23], v[166:167]
	v_pk_mul_f32 v[18:19], v[18:19], v[170:171]

; #define SBAR() __builtin_amdgcn_sched_barrier(0)
; #define NPUB() do { asm volatile("s_waitcnt vmcnt(0)" ::: "memory"); __syncthreads(); } while (0)
; template <bool NA> __device__ __forceinline__ void acc_init(f32x16& p0, f32x16& p1, int j, const Unit& U, int wid, int r32, int hi) {
;   if constexpr (!NA) { p0 = f32x16{}; p1 = f32x16{}; }
;   else {
;     int slice = 16;
;     if (j >= U.nsplit) { const int kr = U.kr0 + (j - U.nsplit), qr_ = U.qrow0 + (wid >> 1); int rs = qr_ - 4; rs = rs < 0 ? 0 : (rs > 248 ? 248 : rs);
;       slice = (kr >= rs && kr < rs + 8) ? (kr - qr_ + 7) : 15; }
;     const float* tb = U.natab + (size_t)slice * 4096 + (unsigned)(((wid & 1) * 32 + r32) * 64 + 4 * hi);
; #pragma unroll
;     for (int q = 0; q < 4; ++q) { const f32x4 a = *(const f32x4*)(tb + 8 * q), b = *(const f32x4*)(tb + 32 + 8 * q);
;       p0[4 * q + 0] = a[0]; p0[4 * q + 1] = a[1]; p0[4 * q + 2] = a[2]; p0[4 * q + 3] = a[3];
;       p1[4 * q + 0] = b[0]; p1[4 * q + 1] = b[1]; p1[4 * q + 2] = b[2]; p1[4 * q + 3] = b[3]; }
;   }
; }
; template <bool NA> __device__ __forceinline__ void unit_body_v128(const Unit& U, char* lds) {
;     ...
;   const int NT = U.nt;
;   NDMA(0, 0); NPUB();
;   for (int j = 0; j < NT; j += 2) {
;     f32x16 p0, p1;
;     acc_init<NA>(p0, p1, j, U, wid, r32, hi); SBAR();
;     NDMA(j + 1, 1); SBAR();
;     NTILE(0); SBAR(); NPUB();
;     acc_init<NA>(p0, p1, j + 1, U, wid, r32, hi); SBAR();
;     if (j + 2 < NT) NDMA(j + 2, 0); SBAR();
;     NTILE(1); SBAR(); NPUB();
.LBB0_1421:
	v_lshl_add_u64 v[78:79], s[6:7], 2, v[136:137]
	global_load_dwordx4 v[82:85], v[78:79], off
	global_load_dwordx4 v[86:89], v[78:79], off offset:32
	global_load_dwordx4 v[66:69], v[78:79], off offset:128
	global_load_dwordx4 v[70:73], v[78:79], off offset:160
	global_load_dwordx4 v[90:93], v[78:79], off offset:64
	global_load_dwordx4 v[94:97], v[78:79], off offset:96
	global_load_dwordx4 v[74:77], v[78:79], off offset:192
	s_nop 0
	global_load_dwordx4 v[78:81], v[78:79], off offset:224
	s_cmp_ge_u32 s4, s96
	s_cselect_b64 s[80:81], -1, 0
	s_and_b64 vcc, exec, s[80:81]
	s_cmp_lt_u32 s4, s28
	s_cselect_b32 s6, s5, s58
	s_mul_i32 s82, s6, 0x3000
	s_mul_hi_i32 s58, s6, 0x3000
	s_add_u32 s6, s24, s82
	s_addc_u32 s7, s25, s58
	s_add_u32 s82, s22, s82
	s_mov_b32 m0, s63
	s_addc_u32 s83, s23, s58
	v_lshl_add_u64 v[158:159], v[0:1], 1, s[6:7]
	global_load_lds_dwordx4 v[158:159], off
	v_lshl_add_u64 v[158:159], v[130:131], 1, s[82:83]
	s_mov_b32 m0, s30
	s_nop 0
	global_load_lds_dwordx4 v[158:159], off
	v_lshl_add_u64 v[158:159], v[132:133], 1, s[6:7]
	s_mov_b32 m0, s97
	s_nop 0
	global_load_lds_dwordx4 v[158:159], off
	v_lshl_add_u64 v[158:159], v[134:135], 1, s[82:83]
	s_mov_b32 m0, s21
	s_nop 0
	global_load_lds_dwordx4 v[158:159], off
.LBB0_1423:
	s_waitcnt lgkmcnt(0)
	ds_read_b128 v[158:161], v143 offset:0x4000
	ds_read_b128 v[162:165], v143 offset:0x6000
	ds_read_b128 v[166:169], v144 offset:0x4000
	ds_read_b128 v[170:173], v144 offset:0x6000
	s_waitcnt lgkmcnt(2)
	s_waitcnt vmcnt(4)
	v_mfma_f32_32x32x16_bf16 v[82:97], v[158:161], v[98:101], v[82:97]
	v_mfma_f32_32x32x16_bf16 v[66:81], v[162:165], v[98:101], v[66:81]
	ds_read_b128 v[158:161], v145 offset:0x4000
	ds_read_b128 v[162:165], v145 offset:0x6000
	s_waitcnt lgkmcnt(2)
	v_mfma_f32_32x32x16_bf16 v[82:97], v[166:169], v[102:105], v[82:97]
	v_mfma_f32_32x32x16_bf16 v[66:81], v[170:173], v[102:105], v[66:81]
	ds_read_b128 v[166:169], v147 offset:0x4000
	ds_read_b128 v[170:173], v147 offset:0x6000
	s_waitcnt lgkmcnt(2)
	v_mfma_f32_32x32x16_bf16 v[82:97], v[158:161], v[106:109], v[82:97]
	v_mfma_f32_32x32x16_bf16 v[66:81], v[162:165], v[106:109], v[66:81]
	ds_read_b128 v[158:161], v148 offset:0x4000
	ds_read_b128 v[162:165], v148 offset:0x6000
	s_waitcnt lgkmcnt(2)
	v_mfma_f32_32x32x16_bf16 v[82:97], v[166:169], v[110:113], v[82:97]
	v_mfma_f32_32x32x16_bf16 v[66:81], v[170:173], v[110:113], v[66:81]
	ds_read_b128 v[166:169], v149 offset:0x4000
	ds_read_b128 v[170:173], v149 offset:0x6000
	s_waitcnt lgkmcnt(2)
	v_mfma_f32_32x32x16_bf16 v[82:97], v[158:161], v[114:117], v[82:97]
	v_mfma_f32_32x32x16_bf16 v[66:81], v[162:165], v[114:117], v[66:81]
	ds_read_b128 v[158:161], v150 offset:0x4000
	ds_read_b128 v[162:165], v150 offset:0x6000
	s_waitcnt lgkmcnt(2)
	v_mfma_f32_32x32x16_bf16 v[82:97], v[166:169], v[118:121], v[82:97]
	v_mfma_f32_32x32x16_bf16 v[66:81], v[170:173], v[118:121], v[66:81]
	ds_read_b128 v[166:169], v151 offset:0x4000
	ds_read_b128 v[170:173], v151 offset:0x6000
	s_waitcnt lgkmcnt(2)
	v_mfma_f32_32x32x16_bf16 v[82:97], v[158:161], v[122:125], v[82:97]
	v_mfma_f32_32x32x16_bf16 v[66:81], v[162:165], v[122:125], v[66:81]
	s_waitcnt lgkmcnt(0)
	v_mfma_f32_32x32x16_bf16 v[82:97], v[166:169], v[126:129], v[82:97]
	v_mfma_f32_32x32x16_bf16 v[66:81], v[170:173], v[126:129], v[66:81]
	s_nop 10
	v_max_f32_e32 v158, v83, v83
	v_max_f32_e32 v159, v82, v82
	v_max_f32_e32 v158, v159, v158
	v_max3_f32 v158, v158, v84, v85
	v_max3_f32 v158, v158, v86, v87
	v_max3_f32 v158, v158, v88, v89
	v_max3_f32 v158, v158, v90, v91
	v_max3_f32 v158, v158, v92, v93
	v_max3_f32 v158, v158, v94, v95
	v_max3_f32 v158, v158, v96, v97
	v_max3_f32 v158, v158, v66, v67
	v_max3_f32 v158, v158, v68, v69
	v_max3_f32 v158, v158, v70, v71
	v_max3_f32 v158, v158, v72, v73
	v_max3_f32 v158, v158, v74, v75
	v_max3_f32 v158, v158, v76, v77
	v_max3_f32 v158, v158, v78, v79
	v_max3_f32 v158, v158, v80, v81
	v_mov_b32_e32 v159, v158
	s_nop 1
	v_permlane32_swap_b32_e32 v158, v159
	v_max_f32_e32 v159, v159, v159
	v_max_f32_e32 v158, v158, v158
	v_max_f32_e32 v158, v158, v159
	v_sub_f32_e32 v159, v158, v155
	v_cmp_ge_f32_e32 vcc, s95, v159
	v_max_f32_e32 v159, v155, v155
	v_max_f32_e32 v159, v159, v158
	v_sub_f32_e32 v158, v155, v159
	v_mul_f32_e32 v158, 0x3e0293ee, v158
	v_exp_f32_e32 v158, v158
	s_cmp_eq_u64 vcc, exec
	s_cselect_b64 s[6:7], -1, 0
	v_cndmask_b32_e64 v158, v158, 1.0, s[6:7]
	v_cmp_gt_f32_e32 vcc, 1.0, v158
	s_cbranch_vccz .LBB0_1412
	s_and_saveexec_b64 s[82:83], s[0:1]
	s_cbranch_execz .LBB0_1411
	ds_write_b32 v146, v158 offset:128
	s_branch .LBB0_1411
